# norm_rows16 loops: counted vmcnt wait moved from right after the next-row loads to the register copies at the loop bottom
# speedup vs baseline: 1.0116x; 1.0018x over previous
; template <bool F32OUT> __device__ __forceinline__ void norm_rows16(const bf16_t* X, const float* __restrict__ g, void* out, int rows) {
;     int bid_ = blockIdx.x, gdim_ = gridDim.x; asm volatile("" : "+s"(bid_), "+s"(gdim_));
;     int tix_ = threadIdx.x; asm volatile("" : "+v"(tix_));
;     const int lane = tix_ & 63, gw = __builtin_amdgcn_readfirstlane(bid_ * 8 + (tix_ >> 6)), GW = gdim_ * 8;
;     float4 ga[4], gb[4];
; #pragma unroll
;     for (int i = 0; i < 4; ++i) { ga[i] = *(const float4*)(g + 8 * lane + 512 * i); gb[i] = *(const float4*)(g + 8 * lane + 512 * i + 4); }
;     const int xl_ = bid_ & 7, chunk_ = rows >> 3, GWx = GW >> 3;
;     const int rend = chunk_ * (xl_ + 1);
;     int row = chunk_ * xl_ + ((bid_ >> 3) * 8 + (gw - bid_ * 8)); u32x4 x[4];
;     if (row < rend) {
; #pragma unroll
;         for (int i = 0; i < 4; ++i) x[i] = *(const u32x4*)(X + (size_t)row * DM + 8 * lane + 512 * i); }
;     while (row < rend) {
;         const int nrow = row + GWx; u32x4 xn[4];
;         if (nrow < rend) {
; #pragma unroll
;             for (int i = 0; i < 4; ++i) xn[i] = *(const u32x4*)(X + (size_t)nrow * DM + 8 * lane + 512 * i); }
.LBB0_212:
	s_or_b64 exec, exec, s[4:5]
	s_mov_b64 s[6:7], s[0:1]
	s_mov_b32 s4, s2
	s_mov_b32 s5, s40
	s_waitcnt lgkmcnt(0)
	s_barrier
	s_mov_b32 s4, s40
	s_mov_b32 s5, s2
	v_mov_b32_e32 v10, v228
	s_lshl_b32 s8, s5, 3
	v_ashrrev_i32_e32 v0, 6, v10
	v_add_u32_e32 v0, s8, v0
	s_and_b32 s10, s5, -8
	v_readfirstlane_b32 s9, v0
	s_sub_i32 s8, s9, s8
	s_add_i32 s10, s8, s10
	s_cmpk_gt_i32 s10, 0x7ff
	s_cbranch_scc1 .LBB0_217
	s_load_dwordx2 s[12:13], s[6:7], 0x28
	s_load_dwordx2 s[8:9], s[6:7], 0xa8
	v_lshlrev_b32_e32 v0, 3, v10
	v_and_b32_e32 v11, 0x1f8, v0
	s_lshl_b32 s5, s5, 11
	v_lshlrev_b32_e32 v8, 2, v11
	v_mov_b32_e32 v9, 0
	s_and_b32 s5, s5, 0x3800
	s_waitcnt lgkmcnt(0)
	v_lshl_add_u64 v[28:29], s[12:13], 0, v[8:9]
	global_load_dwordx4 v[0:3], v8, s[12:13]
	global_load_dwordx4 v[4:7], v8, s[12:13] offset:16
	global_load_dwordx4 v[12:15], v8, s[12:13] offset:2048
	global_load_dwordx4 v[16:19], v8, s[12:13] offset:2064
	s_mov_b64 s[6:7], 0x1000
	s_add_i32 s12, s5, 0x800
	v_lshl_add_u64 v[30:31], v[28:29], 0, s[6:7]
	s_mov_b64 s[6:7], 0x1800
	s_add_u32 s14, s8, 0x2dd24000
	v_lshl_add_u64 v[38:39], v[28:29], 0, s[6:7]
	s_addc_u32 s15, s9, 0
	s_add_i32 s6, s10, s5
	s_ashr_i32 s7, s6, 31
	s_lshl_b64 s[10:11], s[6:7], 12
	v_add_co_u32_e32 v36, vcc, 0x1000, v28
	s_add_u32 s16, s14, s10
	s_nop 0
	v_addc_co_u32_e32 v37, vcc, 0, v29, vcc
	s_addc_u32 s17, s15, s11
	v_lshlrev_b32_e32 v8, 1, v11
	global_load_dwordx4 v[20:23], v[36:37], off
	global_load_dwordx4 v[24:27], v[30:31], off offset:16
	s_nop 0
	global_load_dwordx4 v[28:31], v[36:37], off offset:2048
	global_load_dwordx4 v[32:35], v[38:39], off offset:16
	global_load_dwordx4 v[60:63], v8, s[16:17]
	global_load_dwordx4 v[56:59], v8, s[16:17] offset:1024
	global_load_dwordx4 v[52:55], v8, s[16:17] offset:2048
	global_load_dwordx4 v[48:51], v8, s[16:17] offset:3072
	v_lshl_add_u64 v[64:65], s[14:15], 0, v[8:9]
	v_mbcnt_hi_u32_b32 v8, -1, v229
	v_and_b32_e32 v11, 64, v8
	v_add_u32_e32 v11, 64, v11
	v_xor_b32_e32 v36, 32, v8
	v_cmp_lt_i32_e32 vcc, v36, v11
	s_add_u32 s8, s8, s10
	s_addc_u32 s9, s9, s11
	v_cndmask_b32_e32 v36, v8, v36, vcc
	v_lshlrev_b32_e32 v68, 2, v36
	v_xor_b32_e32 v36, 16, v8
	v_cmp_lt_i32_e32 vcc, v36, v11
	s_ashr_i32 s5, s4, 31
	v_mov_b32_e32 v74, 0x358637bd
	v_cndmask_b32_e32 v36, v8, v36, vcc
	v_lshlrev_b32_e32 v69, 2, v36
	v_xor_b32_e32 v36, 8, v8
	v_cmp_lt_i32_e32 vcc, v36, v11
	v_mov_b32_e32 v37, v9
	v_mov_b32_e32 v38, v9
	v_cndmask_b32_e32 v36, v8, v36, vcc
	v_lshlrev_b32_e32 v70, 2, v36
	v_xor_b32_e32 v36, 4, v8
	v_cmp_lt_i32_e32 vcc, v36, v11
	v_mov_b32_e32 v39, v9
	v_mov_b32_e32 v40, v9
	v_cndmask_b32_e32 v36, v8, v36, vcc
	v_lshlrev_b32_e32 v71, 2, v36
	v_xor_b32_e32 v36, 2, v8
	v_cmp_lt_i32_e32 vcc, v36, v11
	v_mov_b32_e32 v41, v9
	v_mov_b32_e32 v42, v9
	v_cndmask_b32_e32 v36, v8, v36, vcc
	v_lshlrev_b32_e32 v72, 2, v36
	v_xor_b32_e32 v36, 1, v8
	v_cmp_lt_i32_e32 vcc, v36, v11
	v_mov_b32_e32 v43, v9
	v_mov_b32_e32 v44, v9
	v_cndmask_b32_e32 v8, v8, v36, vcc
	v_lshlrev_b32_e32 v73, 2, v8
	v_and_b32_e32 v8, 63, v10
	v_lshlrev_b32_e32 v8, 4, v8
	v_lshl_add_u64 v[10:11], s[8:9], 0, v[8:9]
	s_mov_b64 s[8:9], 0xc700000
	v_lshl_add_u64 v[66:67], v[10:11], 0, s[8:9]
	s_lshl_b64 s[8:9], s[4:5], 12
	s_mov_b32 s5, 0x800000
	v_mov_b32_e32 v8, v9
	v_mov_b32_e32 v10, v9
	v_mov_b32_e32 v11, v9
	v_mov_b32_e32 v36, v9
	v_mov_b32_e32 v45, v9
	v_mov_b32_e32 v46, v9
	v_mov_b32_e32 v47, v9
	s_waitcnt vmcnt(0)
	s_branch .LBB0_215
; __device__ __forceinline__ unsigned cvt_pk_bf16(float lo, float hi) { unsigned r; asm volatile("v_cvt_pk_bf16_f32 %0, %1, %2" : "=v"(r) : "v"(lo), "v"(hi)); return r; }
; __device__ __forceinline__ float bflo(unsigned w) { return __uint_as_float(w << 16); }
; __device__ __forceinline__ float bfhi(unsigned w) { return __uint_as_float(w & 0xffff0000u); }
; template <bool F32OUT> __device__ __forceinline__ void norm_rows16(const bf16_t* X, const float* __restrict__ g, void* out, int rows) {
;     ...
;     while (row < rend) {
;         const int nrow = row + GWx; u32x4 xn[4];
;         if (nrow < rend) {
; #pragma unroll
;             for (int i = 0; i < 4; ++i) xn[i] = *(const u32x4*)(X + (size_t)nrow * DM + 8 * lane + 512 * i); }
;         float v[4][8]; float ss = 0.f;
; #pragma unroll
;         for (int i = 0; i < 4; ++i) { v[i][0] = bflo(x[i].x); v[i][1] = bfhi(x[i].x); v[i][2] = bflo(x[i].y); v[i][3] = bfhi(x[i].y); v[i][4] = bflo(x[i].z); v[i][5] = bfhi(x[i].z); v[i][6] = bflo(x[i].w); v[i][7] = bfhi(x[i].w);
; #pragma unroll
;             for (int e = 0; e < 8; ++e) ss += v[i][e] * v[i][e]; }
;         ss = wave_sum(ss);
;         const float rstd = rsqrtf(ss * (1.0f / DM) + 1e-6f);
; #pragma unroll
;         for (int i = 0; i < 4; ++i) {
;             const float o0 = v[i][0] * rstd * ga[i].x, o1 = v[i][1] * rstd * ga[i].y, o2 = v[i][2] * rstd * ga[i].z, o3 = v[i][3] * rstd * ga[i].w;
;             const float o4 = v[i][4] * rstd * gb[i].x, o5 = v[i][5] * rstd * gb[i].y, o6 = v[i][6] * rstd * gb[i].z, o7 = v[i][7] * rstd * gb[i].w;
;             if (F32OUT) { float* op = (float*)out + (size_t)row * DM + 8 * lane + 512 * i; *(float4*)op = make_float4(o0, o1, o2, o3); *(float4*)(op + 4) = make_float4(o4, o5, o6, o7); }
;             else { u32x4 w; w.x = cvt_pk_bf16(o0, o1); w.y = cvt_pk_bf16(o2, o3); w.z = cvt_pk_bf16(o4, o5); w.w = cvt_pk_bf16(o6, o7); *(u32x4*)((bf16_t*)out + (size_t)row * DM + 8 * lane + 512 * i) = w; }
;         }
; #pragma unroll
;         for (int i = 0; i < 4; ++i) x[i] = xn[i];
;         row = nrow;
;     }
.LBB0_214:
	v_lshlrev_b32_e32 v75, 16, v60
	v_and_b32_e32 v60, 0xffff0000, v60
	v_mul_f32_e32 v79, v60, v60
	v_lshlrev_b32_e32 v76, 16, v61
	v_fmac_f32_e32 v79, v75, v75
	v_and_b32_e32 v61, 0xffff0000, v61
	v_fmac_f32_e32 v79, v76, v76
	v_lshlrev_b32_e32 v77, 16, v62
	v_fmac_f32_e32 v79, v61, v61
	v_and_b32_e32 v62, 0xffff0000, v62
	v_fmac_f32_e32 v79, v77, v77
	v_lshlrev_b32_e32 v78, 16, v63
	v_fmac_f32_e32 v79, v62, v62
	v_and_b32_e32 v63, 0xffff0000, v63
	v_fmac_f32_e32 v79, v78, v78
	v_fmac_f32_e32 v79, v63, v63
	v_lshlrev_b32_e32 v80, 16, v56
	v_and_b32_e32 v56, 0xffff0000, v56
	v_fmac_f32_e32 v79, v80, v80
	v_lshlrev_b32_e32 v81, 16, v57
	v_fmac_f32_e32 v79, v56, v56
	v_and_b32_e32 v57, 0xffff0000, v57
	v_fmac_f32_e32 v79, v81, v81
	v_lshlrev_b32_e32 v82, 16, v58
	v_fmac_f32_e32 v79, v57, v57
	v_and_b32_e32 v58, 0xffff0000, v58
	v_fmac_f32_e32 v79, v82, v82
	v_lshlrev_b32_e32 v83, 16, v59
	v_fmac_f32_e32 v79, v58, v58
	v_and_b32_e32 v59, 0xffff0000, v59
	v_fmac_f32_e32 v79, v83, v83
	v_fmac_f32_e32 v79, v59, v59
	v_lshlrev_b32_e32 v84, 16, v52
	v_and_b32_e32 v85, 0xffff0000, v52
	v_fmac_f32_e32 v79, v84, v84
	v_lshlrev_b32_e32 v86, 16, v53
	v_fmac_f32_e32 v79, v85, v85
	v_and_b32_e32 v87, 0xffff0000, v53
	v_fmac_f32_e32 v79, v86, v86
	v_lshlrev_b32_e32 v88, 16, v54
	v_fmac_f32_e32 v79, v87, v87
	v_and_b32_e32 v89, 0xffff0000, v54
	v_fmac_f32_e32 v79, v88, v88
	v_lshlrev_b32_e32 v90, 16, v55
	v_fmac_f32_e32 v79, v89, v89
	v_and_b32_e32 v91, 0xffff0000, v55
	v_fmac_f32_e32 v79, v90, v90
	v_fmac_f32_e32 v79, v91, v91
	v_lshlrev_b32_e32 v92, 16, v48
	v_and_b32_e32 v93, 0xffff0000, v48
	v_fmac_f32_e32 v79, v92, v92
	v_lshlrev_b32_e32 v94, 16, v49
	v_fmac_f32_e32 v79, v93, v93
	v_and_b32_e32 v95, 0xffff0000, v49
	v_fmac_f32_e32 v79, v94, v94
	v_and_b32_e32 v52, 0xffff0000, v50
	v_lshlrev_b32_e32 v53, 16, v50
	v_fmac_f32_e32 v79, v95, v95
	v_pk_mul_f32 v[48:49], v[52:53], v[52:53]
	v_and_b32_e32 v54, 0xffff0000, v51
	v_add_f32_e32 v49, v49, v79
	v_lshlrev_b32_e32 v55, 16, v51
	v_add_f32_e32 v50, v48, v49
	v_pk_mul_f32 v[48:49], v[54:55], v[54:55]
	s_nop 0
	v_add_f32_e32 v49, v49, v50
	v_add_f32_e32 v48, v48, v49
	ds_bpermute_b32 v49, v68, v48
	s_waitcnt lgkmcnt(0)
	v_add_f32_e32 v48, v48, v49
	ds_bpermute_b32 v49, v69, v48
	s_waitcnt lgkmcnt(0)
	v_add_f32_e32 v48, v48, v49
	ds_bpermute_b32 v49, v70, v48
	s_waitcnt lgkmcnt(0)
	v_add_f32_e32 v48, v48, v49
	ds_bpermute_b32 v49, v71, v48
	s_waitcnt lgkmcnt(0)
	v_add_f32_e32 v48, v48, v49
	ds_bpermute_b32 v49, v72, v48
	s_waitcnt lgkmcnt(0)
	v_add_f32_e32 v48, v48, v49
	ds_bpermute_b32 v49, v73, v48
	s_waitcnt lgkmcnt(0)
	v_add_f32_e32 v48, v48, v49
	v_fmamk_f32 v48, v48, 0x3a000000, v74
	v_mul_f32_e32 v49, 0x4b800000, v48
	v_cmp_gt_f32_e32 vcc, s5, v48
	s_nop 1
	v_cndmask_b32_e32 v48, v48, v49, vcc
	v_rsq_f32_e32 v48, v48
	s_nop 0
	v_mul_f32_e32 v49, 0x45800000, v48
	v_cndmask_b32_e32 v79, v48, v49, vcc
	v_mul_f32_e32 v48, v79, v75
	v_mul_f32_e32 v49, v79, v60
	v_mul_f32_e32 v50, v79, v76
	v_mul_f32_e32 v51, v79, v61
	v_mul_f32_e32 v48, v0, v48
	v_mul_f32_e32 v49, v1, v49
	v_mul_f32_e32 v50, v2, v50
	v_mul_f32_e32 v51, v3, v51
	v_mul_f32_e32 v60, v79, v77
	v_mul_f32_e32 v61, v79, v62
	v_mul_f32_e32 v62, v79, v78
	v_mul_f32_e32 v63, v79, v63
	v_mul_f32_e32 v60, v4, v60
	v_mul_f32_e32 v61, v5, v61
	v_mul_f32_e32 v62, v6, v62
	v_mul_f32_e32 v63, v7, v63
	v_cvt_pk_bf16_f32 v48, v48, v49
	v_cvt_pk_bf16_f32 v49, v50, v51
	v_cvt_pk_bf16_f32 v50, v60, v61
	v_cvt_pk_bf16_f32 v51, v62, v63
	global_store_dwordx4 v[66:67], v[48:51], off
	v_mul_f32_e32 v59, v79, v59
	v_mul_f32_e32 v59, v19, v59
	v_mul_f32_e32 v48, v79, v80
	v_mul_f32_e32 v49, v79, v56
	v_mul_f32_e32 v50, v79, v81
	v_mul_f32_e32 v51, v79, v57
	v_mul_f32_e32 v48, v12, v48
	v_mul_f32_e32 v49, v13, v49
	v_mul_f32_e32 v50, v14, v50
	v_mul_f32_e32 v51, v15, v51
	v_mul_f32_e32 v56, v79, v82
	v_mul_f32_e32 v57, v79, v58
	v_mul_f32_e32 v58, v79, v83
	v_mul_f32_e32 v56, v16, v56
	v_mul_f32_e32 v57, v17, v57
	v_mul_f32_e32 v58, v18, v58
	v_cvt_pk_bf16_f32 v48, v48, v49
	v_cvt_pk_bf16_f32 v49, v50, v51
	v_cvt_pk_bf16_f32 v50, v56, v57
	v_cvt_pk_bf16_f32 v51, v58, v59
	global_store_dwordx4 v[66:67], v[48:51], off offset:1024
	v_mul_f32_e32 v56, v79, v88
	v_mul_f32_e32 v57, v79, v89
	v_mul_f32_e32 v48, v79, v84
	v_mul_f32_e32 v49, v79, v85
	v_mul_f32_e32 v50, v79, v86
	v_mul_f32_e32 v51, v79, v87
	v_mul_f32_e32 v48, v20, v48
	v_mul_f32_e32 v49, v21, v49
	v_mul_f32_e32 v50, v22, v50
	v_mul_f32_e32 v51, v23, v51
	v_mul_f32_e32 v58, v79, v90
	v_mul_f32_e32 v59, v79, v91
	v_mul_f32_e32 v56, v24, v56
	v_mul_f32_e32 v57, v25, v57
	v_mul_f32_e32 v58, v26, v58
	v_mul_f32_e32 v59, v27, v59
	v_cvt_pk_bf16_f32 v48, v48, v49
	v_cvt_pk_bf16_f32 v49, v50, v51
	v_cvt_pk_bf16_f32 v50, v56, v57
	v_cvt_pk_bf16_f32 v51, v58, v59
	global_store_dwordx4 v[66:67], v[48:51], off offset:2048
	v_mul_f32_e32 v53, v79, v53
	v_mul_f32_e32 v52, v79, v52
	v_mul_f32_e32 v48, v79, v92
	v_mul_f32_e32 v49, v79, v93
	v_mul_f32_e32 v50, v79, v94
	v_mul_f32_e32 v51, v79, v95
	v_mul_f32_e32 v48, v28, v48
	v_mul_f32_e32 v49, v29, v49
	v_mul_f32_e32 v50, v30, v50
	v_mul_f32_e32 v51, v31, v51
	v_mul_f32_e32 v55, v79, v55
	v_mul_f32_e32 v54, v79, v54
	v_mul_f32_e32 v53, v32, v53
	v_mul_f32_e32 v52, v33, v52
	v_mul_f32_e32 v55, v34, v55
	v_mul_f32_e32 v54, v35, v54
	v_cvt_pk_bf16_f32 v48, v48, v49
	v_cvt_pk_bf16_f32 v49, v50, v51
	v_cvt_pk_bf16_f32 v50, v53, v52
	v_cvt_pk_bf16_f32 v51, v55, v54
	global_store_dwordx4 v[66:67], v[48:51], off offset:3072
	v_lshl_add_u64 v[66:67], v[66:67], 0, s[8:9]
	s_andn2_b64 vcc, exec, s[10:11]
	s_waitcnt vmcnt(4)
	v_mov_b32_e32 v60, v8
	v_mov_b32_e32 v61, v9
	v_mov_b32_e32 v62, v10
	v_mov_b32_e32 v63, v11
	v_mov_b32_e32 v56, v36
	v_mov_b32_e32 v57, v37
	v_mov_b32_e32 v58, v38
	v_mov_b32_e32 v59, v39
	v_mov_b32_e32 v52, v40
	v_mov_b32_e32 v53, v41
	v_mov_b32_e32 v54, v42
	v_mov_b32_e32 v55, v43
	v_mov_b32_e32 v48, v44
	v_mov_b32_e32 v49, v45
	v_mov_b32_e32 v50, v46
	v_mov_b32_e32 v51, v47
	s_cbranch_vccz .LBB0_217

; template <bool F32OUT> __device__ __forceinline__ void norm_rows16(const bf16_t* X, const float* __restrict__ g, void* out, int rows) {
;     int bid_ = blockIdx.x, gdim_ = gridDim.x; asm volatile("" : "+s"(bid_), "+s"(gdim_));
;     int tix_ = threadIdx.x; asm volatile("" : "+v"(tix_));
;     const int lane = tix_ & 63, gw = __builtin_amdgcn_readfirstlane(bid_ * 8 + (tix_ >> 6)), GW = gdim_ * 8;
;     float4 ga[4], gb[4];
; #pragma unroll
;     for (int i = 0; i < 4; ++i) { ga[i] = *(const float4*)(g + 8 * lane + 512 * i); gb[i] = *(const float4*)(g + 8 * lane + 512 * i + 4); }
;     const int xl_ = bid_ & 7, chunk_ = rows >> 3, GWx = GW >> 3;
;     const int rend = chunk_ * (xl_ + 1);
;     int row = chunk_ * xl_ + ((bid_ >> 3) * 8 + (gw - bid_ * 8)); u32x4 x[4];
;     if (row < rend) {
; #pragma unroll
;         for (int i = 0; i < 4; ++i) x[i] = *(const u32x4*)(X + (size_t)row * DM + 8 * lane + 512 * i); }
;     while (row < rend) {
;         const int nrow = row + GWx; u32x4 xn[4];
;         if (nrow < rend) {
; #pragma unroll
;             for (int i = 0; i < 4; ++i) xn[i] = *(const u32x4*)(X + (size_t)nrow * DM + 8 * lane + 512 * i); }
.LBB0_840:
	s_or_b64 exec, exec, s[4:5]
	s_mov_b64 s[6:7], s[0:1]
	s_mov_b32 s4, s2
	s_mov_b32 s5, s40
	s_waitcnt lgkmcnt(0)
	s_barrier
	s_mov_b32 s4, s40
	s_mov_b32 s5, s2
	v_mov_b32_e32 v10, v228
	s_lshl_b32 s8, s5, 3
	v_ashrrev_i32_e32 v0, 6, v10
	v_add_u32_e32 v0, s8, v0
	s_and_b32 s10, s5, -8
	v_readfirstlane_b32 s9, v0
	s_sub_i32 s8, s9, s8
	s_add_i32 s10, s8, s10
	s_cmpk_gt_i32 s10, 0x7ff
	s_cbranch_scc1 .LBB0_845
	s_load_dwordx2 s[12:13], s[6:7], 0x80
	s_load_dwordx2 s[8:9], s[6:7], 0xa8
	v_lshlrev_b32_e32 v0, 3, v10
	v_and_b32_e32 v11, 0x1f8, v0
	s_lshl_b32 s5, s5, 11
	v_lshlrev_b32_e32 v8, 2, v11
	v_mov_b32_e32 v9, 0
	s_and_b32 s5, s5, 0x3800
	s_waitcnt lgkmcnt(0)
	v_lshl_add_u64 v[28:29], s[12:13], 0, v[8:9]
	global_load_dwordx4 v[0:3], v8, s[12:13]
	global_load_dwordx4 v[4:7], v8, s[12:13] offset:16
	global_load_dwordx4 v[12:15], v8, s[12:13] offset:2048
	global_load_dwordx4 v[16:19], v8, s[12:13] offset:2064
	s_mov_b64 s[6:7], 0x1000
	s_add_i32 s12, s5, 0x800
	v_lshl_add_u64 v[30:31], v[28:29], 0, s[6:7]
	s_mov_b64 s[6:7], 0x1800
	s_add_u32 s14, s8, 0x2dd24000
	v_lshl_add_u64 v[38:39], v[28:29], 0, s[6:7]
	s_addc_u32 s15, s9, 0
	s_add_i32 s6, s10, s5
	s_ashr_i32 s7, s6, 31
	s_lshl_b64 s[10:11], s[6:7], 12
	v_add_co_u32_e32 v36, vcc, 0x1000, v28
	s_add_u32 s16, s14, s10
	s_nop 0
	v_addc_co_u32_e32 v37, vcc, 0, v29, vcc
	s_addc_u32 s17, s15, s11
	v_lshlrev_b32_e32 v8, 1, v11
	global_load_dwordx4 v[20:23], v[36:37], off
	global_load_dwordx4 v[24:27], v[30:31], off offset:16
	s_nop 0
	global_load_dwordx4 v[28:31], v[36:37], off offset:2048
	global_load_dwordx4 v[32:35], v[38:39], off offset:16
	global_load_dwordx4 v[60:63], v8, s[16:17]
	global_load_dwordx4 v[56:59], v8, s[16:17] offset:1024
	global_load_dwordx4 v[52:55], v8, s[16:17] offset:2048
	global_load_dwordx4 v[48:51], v8, s[16:17] offset:3072
	v_lshl_add_u64 v[64:65], s[14:15], 0, v[8:9]
	v_mbcnt_hi_u32_b32 v8, -1, v229
	v_and_b32_e32 v11, 64, v8
	v_add_u32_e32 v11, 64, v11
	v_xor_b32_e32 v36, 32, v8
	v_cmp_lt_i32_e32 vcc, v36, v11
	s_add_u32 s8, s8, s10
	s_addc_u32 s9, s9, s11
	v_cndmask_b32_e32 v36, v8, v36, vcc
	v_lshlrev_b32_e32 v68, 2, v36
	v_xor_b32_e32 v36, 16, v8
	v_cmp_lt_i32_e32 vcc, v36, v11
	s_ashr_i32 s5, s4, 31
	v_mov_b32_e32 v74, 0x358637bd
	v_cndmask_b32_e32 v36, v8, v36, vcc
	v_lshlrev_b32_e32 v69, 2, v36
	v_xor_b32_e32 v36, 8, v8
	v_cmp_lt_i32_e32 vcc, v36, v11
	v_mov_b32_e32 v37, v9
	v_mov_b32_e32 v38, v9
	v_cndmask_b32_e32 v36, v8, v36, vcc
	v_lshlrev_b32_e32 v70, 2, v36
	v_xor_b32_e32 v36, 4, v8
	v_cmp_lt_i32_e32 vcc, v36, v11
	v_mov_b32_e32 v39, v9
	v_mov_b32_e32 v40, v9
	v_cndmask_b32_e32 v36, v8, v36, vcc
	v_lshlrev_b32_e32 v71, 2, v36
	v_xor_b32_e32 v36, 2, v8
	v_cmp_lt_i32_e32 vcc, v36, v11
	v_mov_b32_e32 v41, v9
	v_mov_b32_e32 v42, v9
	v_cndmask_b32_e32 v36, v8, v36, vcc
	v_lshlrev_b32_e32 v72, 2, v36
	v_xor_b32_e32 v36, 1, v8
	v_cmp_lt_i32_e32 vcc, v36, v11
	v_mov_b32_e32 v43, v9
	v_mov_b32_e32 v44, v9
	v_cndmask_b32_e32 v8, v8, v36, vcc
	v_lshlrev_b32_e32 v73, 2, v8
	v_and_b32_e32 v8, 63, v10
	v_lshlrev_b32_e32 v8, 4, v8
	v_lshl_add_u64 v[10:11], s[8:9], 0, v[8:9]
	s_mov_b64 s[8:9], 0xc700000
	v_lshl_add_u64 v[66:67], v[10:11], 0, s[8:9]
	s_lshl_b64 s[8:9], s[4:5], 12
	s_mov_b32 s5, 0x800000
	v_mov_b32_e32 v8, v9
	v_mov_b32_e32 v10, v9
	v_mov_b32_e32 v11, v9
	v_mov_b32_e32 v36, v9
	v_mov_b32_e32 v45, v9
	v_mov_b32_e32 v46, v9
	v_mov_b32_e32 v47, v9
	s_waitcnt vmcnt(0)
	s_branch .LBB0_843

; template <bool F32OUT> __device__ __forceinline__ void norm_rows16(const bf16_t* X, const float* __restrict__ g, void* out, int rows) {
;     int bid_ = blockIdx.x, gdim_ = gridDim.x; asm volatile("" : "+s"(bid_), "+s"(gdim_));
;     int tix_ = threadIdx.x; asm volatile("" : "+v"(tix_));
;     const int lane = tix_ & 63, gw = __builtin_amdgcn_readfirstlane(bid_ * 8 + (tix_ >> 6)), GW = gdim_ * 8;
;     float4 ga[4], gb[4];
; #pragma unroll
;     for (int i = 0; i < 4; ++i) { ga[i] = *(const float4*)(g + 8 * lane + 512 * i); gb[i] = *(const float4*)(g + 8 * lane + 512 * i + 4); }
;     const int xl_ = bid_ & 7, chunk_ = rows >> 3, GWx = GW >> 3;
;     const int rend = chunk_ * (xl_ + 1);
;     int row = chunk_ * xl_ + ((bid_ >> 3) * 8 + (gw - bid_ * 8)); u32x4 x[4];
;     if (row < rend) {
; #pragma unroll
;         for (int i = 0; i < 4; ++i) x[i] = *(const u32x4*)(X + (size_t)row * DM + 8 * lane + 512 * i); }
;     while (row < rend) {
;         const int nrow = row + GWx; u32x4 xn[4];
;         if (nrow < rend) {
; #pragma unroll
;             for (int i = 0; i < 4; ++i) xn[i] = *(const u32x4*)(X + (size_t)nrow * DM + 8 * lane + 512 * i); }
.LBB0_1079:
	s_mov_b32 s5, s2
	s_mov_b32 s4, s40
	s_waitcnt vmcnt(11)
	v_mov_b32_e32 v2, v228
	s_lshl_b32 s6, s5, 3
	v_ashrrev_i32_e32 v0, 6, v2
	v_add_u32_e32 v0, s6, v0
	s_and_b32 s12, s5, -8
	v_readfirstlane_b32 s7, v0
	s_sub_i32 s6, s7, s6
	s_add_i32 s6, s6, s12
	s_cmpk_lt_i32 s6, 0x800
	s_cbranch_scc0 .LBB0_1084
	v_lshlrev_b32_e32 v0, 3, v2
	v_and_b32_e32 v3, 0x1f8, v0
	v_lshlrev_b32_e32 v0, 2, v3
	v_mov_b32_e32 v1, 0
	s_waitcnt vmcnt(4)
	v_lshl_add_u64 v[28:29], s[10:11], 0, v[0:1]
	s_mov_b64 s[10:11], 0x2000
	s_lshl_b32 s5, s5, 11
	v_lshl_add_u64 v[20:21], v[28:29], 0, s[10:11]
	s_mov_b64 s[10:11], 0x3000
	s_and_b32 s5, s5, 0x3800
	v_lshl_add_u64 v[30:31], v[28:29], 0, s[10:11]
	s_mov_b64 s[10:11], 0x3800
	s_add_i32 s14, s5, 0x800
	v_lshl_add_u64 v[38:39], v[28:29], 0, s[10:11]
	s_add_u32 s10, s24, 0x2dd24000
	s_addc_u32 s11, s25, 0
	s_add_i32 s6, s6, s5
	v_add_co_u32_e32 v22, vcc, 0x2000, v28
	s_ashr_i32 s7, s6, 31
	s_nop 0
	v_addc_co_u32_e32 v23, vcc, 0, v29, vcc
	s_lshl_b64 s[12:13], s[6:7], 12
	v_add_co_u32_e32 v36, vcc, 0x3000, v28
	s_add_u32 s18, s10, s12
	s_nop 0
	v_addc_co_u32_e32 v37, vcc, 0, v29, vcc
	s_addc_u32 s19, s11, s13
	v_lshlrev_b32_e32 v0, 1, v3
	global_load_dwordx4 v[4:7], v[20:21], off offset:16
	global_load_dwordx4 v[8:11], v[20:21], off offset:2048
	global_load_dwordx4 v[12:15], v[22:23], off
	global_load_dwordx4 v[16:19], v[20:21], off offset:2064
	s_nop 0
	global_load_dwordx4 v[20:23], v[36:37], off
	global_load_dwordx4 v[24:27], v[30:31], off offset:16
	s_nop 0
	global_load_dwordx4 v[28:31], v[36:37], off offset:2048
	global_load_dwordx4 v[32:35], v[38:39], off offset:16
	global_load_dwordx4 v[60:63], v0, s[18:19]
	global_load_dwordx4 v[56:59], v0, s[18:19] offset:1024
	global_load_dwordx4 v[52:55], v0, s[18:19] offset:2048
	global_load_dwordx4 v[48:51], v0, s[18:19] offset:3072
	v_lshl_add_u64 v[64:65], s[10:11], 0, v[0:1]
	v_mbcnt_hi_u32_b32 v0, -1, v229
	v_and_b32_e32 v3, 64, v0
	v_add_u32_e32 v3, 64, v3
	v_xor_b32_e32 v36, 32, v0
	v_cmp_lt_i32_e32 vcc, v36, v3
	s_add_u32 s10, s24, s12
	s_addc_u32 s11, s25, s13
	v_cndmask_b32_e32 v36, v0, v36, vcc
	v_lshlrev_b32_e32 v68, 2, v36
	v_xor_b32_e32 v36, 16, v0
	v_cmp_lt_i32_e32 vcc, v36, v3
	s_ashr_i32 s5, s4, 31
	v_mov_b32_e32 v74, 0x358637bd
	v_cndmask_b32_e32 v36, v0, v36, vcc
	v_lshlrev_b32_e32 v69, 2, v36
	v_xor_b32_e32 v36, 8, v0
	v_cmp_lt_i32_e32 vcc, v36, v3
	v_mov_b32_e32 v37, v1
	v_mov_b32_e32 v38, v1
	v_cndmask_b32_e32 v36, v0, v36, vcc
	v_lshlrev_b32_e32 v70, 2, v36
	v_xor_b32_e32 v36, 4, v0
	v_cmp_lt_i32_e32 vcc, v36, v3
	v_mov_b32_e32 v39, v1
	v_mov_b32_e32 v40, v1
	v_cndmask_b32_e32 v36, v0, v36, vcc
	v_lshlrev_b32_e32 v71, 2, v36
	v_xor_b32_e32 v36, 2, v0
	v_cmp_lt_i32_e32 vcc, v36, v3
	v_mov_b32_e32 v41, v1
	v_mov_b32_e32 v42, v1
	v_cndmask_b32_e32 v36, v0, v36, vcc
	v_lshlrev_b32_e32 v72, 2, v36
	v_xor_b32_e32 v36, 1, v0
	v_cmp_lt_i32_e32 vcc, v36, v3
	v_mov_b32_e32 v43, v1
	v_mov_b32_e32 v44, v1
	v_cndmask_b32_e32 v0, v0, v36, vcc
	v_lshlrev_b32_e32 v73, 2, v0
	v_and_b32_e32 v0, 63, v2
	v_lshlrev_b32_e32 v0, 4, v0
	v_lshl_add_u64 v[2:3], s[10:11], 0, v[0:1]
	s_mov_b64 s[10:11], 0xc700000
	v_lshl_add_u64 v[66:67], v[2:3], 0, s[10:11]
	s_lshl_b64 s[10:11], s[4:5], 12
	s_mov_b32 s5, 0x800000
	v_mov_b32_e32 v0, v1
	v_mov_b32_e32 v2, v1
	v_mov_b32_e32 v3, v1
	v_mov_b32_e32 v36, v1
	v_mov_b32_e32 v45, v1
	v_mov_b32_e32 v46, v1
	v_mov_b32_e32 v47, v1
	s_waitcnt vmcnt(0)
	s_branch .LBB0_1082
; __device__ __forceinline__ unsigned cvt_pk_bf16(float lo, float hi) { unsigned r; asm volatile("v_cvt_pk_bf16_f32 %0, %1, %2" : "=v"(r) : "v"(lo), "v"(hi)); return r; }
; __device__ __forceinline__ float bflo(unsigned w) { return __uint_as_float(w << 16); }
; __device__ __forceinline__ float bfhi(unsigned w) { return __uint_as_float(w & 0xffff0000u); }
; template <bool F32OUT> __device__ __forceinline__ void norm_rows16(const bf16_t* X, const float* __restrict__ g, void* out, int rows) {
;     ...
;     while (row < rend) {
;         const int nrow = row + GWx; u32x4 xn[4];
;         if (nrow < rend) {
; #pragma unroll
;             for (int i = 0; i < 4; ++i) xn[i] = *(const u32x4*)(X + (size_t)nrow * DM + 8 * lane + 512 * i); }
;         float v[4][8]; float ss = 0.f;
; #pragma unroll
;         for (int i = 0; i < 4; ++i) { v[i][0] = bflo(x[i].x); v[i][1] = bfhi(x[i].x); v[i][2] = bflo(x[i].y); v[i][3] = bfhi(x[i].y); v[i][4] = bflo(x[i].z); v[i][5] = bfhi(x[i].z); v[i][6] = bflo(x[i].w); v[i][7] = bfhi(x[i].w);
; #pragma unroll
;             for (int e = 0; e < 8; ++e) ss += v[i][e] * v[i][e]; }
;         ss = wave_sum(ss);
;         const float rstd = rsqrtf(ss * (1.0f / DM) + 1e-6f);
; #pragma unroll
;         for (int i = 0; i < 4; ++i) {
;             const float o0 = v[i][0] * rstd * ga[i].x, o1 = v[i][1] * rstd * ga[i].y, o2 = v[i][2] * rstd * ga[i].z, o3 = v[i][3] * rstd * ga[i].w;
;             const float o4 = v[i][4] * rstd * gb[i].x, o5 = v[i][5] * rstd * gb[i].y, o6 = v[i][6] * rstd * gb[i].z, o7 = v[i][7] * rstd * gb[i].w;
;             if (F32OUT) { float* op = (float*)out + (size_t)row * DM + 8 * lane + 512 * i; *(float4*)op = make_float4(o0, o1, o2, o3); *(float4*)(op + 4) = make_float4(o4, o5, o6, o7); }
;             else { u32x4 w; w.x = cvt_pk_bf16(o0, o1); w.y = cvt_pk_bf16(o2, o3); w.z = cvt_pk_bf16(o4, o5); w.w = cvt_pk_bf16(o6, o7); *(u32x4*)((bf16_t*)out + (size_t)row * DM + 8 * lane + 512 * i) = w; }
;         }
; #pragma unroll
;         for (int i = 0; i < 4; ++i) x[i] = xn[i];
;         row = nrow;
;     }
.LBB0_1081:
	v_lshlrev_b32_e32 v75, 16, v60
	v_and_b32_e32 v60, 0xffff0000, v60
	v_mul_f32_e32 v79, v60, v60
	v_lshlrev_b32_e32 v76, 16, v61
	v_fmac_f32_e32 v79, v75, v75
	v_and_b32_e32 v61, 0xffff0000, v61
	v_fmac_f32_e32 v79, v76, v76
	v_lshlrev_b32_e32 v77, 16, v62
	v_fmac_f32_e32 v79, v61, v61
	v_and_b32_e32 v62, 0xffff0000, v62
	v_fmac_f32_e32 v79, v77, v77
	v_lshlrev_b32_e32 v78, 16, v63
	v_fmac_f32_e32 v79, v62, v62
	v_and_b32_e32 v63, 0xffff0000, v63
	v_fmac_f32_e32 v79, v78, v78
	v_fmac_f32_e32 v79, v63, v63
	v_lshlrev_b32_e32 v80, 16, v56
	v_and_b32_e32 v56, 0xffff0000, v56
	v_fmac_f32_e32 v79, v80, v80
	v_lshlrev_b32_e32 v81, 16, v57
	v_fmac_f32_e32 v79, v56, v56
	v_and_b32_e32 v57, 0xffff0000, v57
	v_fmac_f32_e32 v79, v81, v81
	v_lshlrev_b32_e32 v82, 16, v58
	v_fmac_f32_e32 v79, v57, v57
	v_and_b32_e32 v58, 0xffff0000, v58
	v_fmac_f32_e32 v79, v82, v82
	v_lshlrev_b32_e32 v83, 16, v59
	v_fmac_f32_e32 v79, v58, v58
	v_and_b32_e32 v59, 0xffff0000, v59
	v_fmac_f32_e32 v79, v83, v83
	v_fmac_f32_e32 v79, v59, v59
	v_lshlrev_b32_e32 v84, 16, v52
	v_and_b32_e32 v85, 0xffff0000, v52
	v_fmac_f32_e32 v79, v84, v84
	v_lshlrev_b32_e32 v86, 16, v53
	v_fmac_f32_e32 v79, v85, v85
	v_and_b32_e32 v87, 0xffff0000, v53
	v_fmac_f32_e32 v79, v86, v86
	v_lshlrev_b32_e32 v88, 16, v54
	v_fmac_f32_e32 v79, v87, v87
	v_and_b32_e32 v89, 0xffff0000, v54
	v_fmac_f32_e32 v79, v88, v88
	v_lshlrev_b32_e32 v90, 16, v55
	v_fmac_f32_e32 v79, v89, v89
	v_and_b32_e32 v91, 0xffff0000, v55
	v_fmac_f32_e32 v79, v90, v90
	v_fmac_f32_e32 v79, v91, v91
	v_lshlrev_b32_e32 v92, 16, v48
	v_and_b32_e32 v93, 0xffff0000, v48
	v_fmac_f32_e32 v79, v92, v92
	v_lshlrev_b32_e32 v94, 16, v49
	v_fmac_f32_e32 v79, v93, v93
	v_and_b32_e32 v95, 0xffff0000, v49
	v_fmac_f32_e32 v79, v94, v94
	v_and_b32_e32 v52, 0xffff0000, v50
	v_lshlrev_b32_e32 v53, 16, v50
	v_fmac_f32_e32 v79, v95, v95
	v_pk_mul_f32 v[48:49], v[52:53], v[52:53]
	v_and_b32_e32 v54, 0xffff0000, v51
	v_add_f32_e32 v49, v49, v79
	v_lshlrev_b32_e32 v55, 16, v51
	v_add_f32_e32 v50, v48, v49
	v_pk_mul_f32 v[48:49], v[54:55], v[54:55]
	s_nop 0
	v_add_f32_e32 v49, v49, v50
	v_add_f32_e32 v48, v48, v49
	ds_bpermute_b32 v49, v68, v48
	s_waitcnt lgkmcnt(0)
	v_add_f32_e32 v48, v48, v49
	ds_bpermute_b32 v49, v69, v48
	s_waitcnt lgkmcnt(0)
	v_add_f32_e32 v48, v48, v49
	ds_bpermute_b32 v49, v70, v48
	s_waitcnt lgkmcnt(0)
	v_add_f32_e32 v48, v48, v49
	ds_bpermute_b32 v49, v71, v48
	s_waitcnt lgkmcnt(0)
	v_add_f32_e32 v48, v48, v49
	ds_bpermute_b32 v49, v72, v48
	s_waitcnt lgkmcnt(0)
	v_add_f32_e32 v48, v48, v49
	ds_bpermute_b32 v49, v73, v48
	s_waitcnt lgkmcnt(0)
	v_add_f32_e32 v48, v48, v49
	v_fmamk_f32 v48, v48, 0x3a000000, v74
	v_mul_f32_e32 v49, 0x4b800000, v48
	v_cmp_gt_f32_e32 vcc, s5, v48
	s_nop 1
	v_cndmask_b32_e32 v48, v48, v49, vcc
	v_rsq_f32_e32 v48, v48
	s_nop 0
	v_mul_f32_e32 v49, 0x45800000, v48
	v_cndmask_b32_e32 v79, v48, v49, vcc
	v_mul_f32_e32 v48, v79, v75
	v_mul_f32_e32 v49, v79, v60
	v_mul_f32_e32 v50, v79, v76
	v_mul_f32_e32 v51, v79, v61
	v_mul_f32_e32 v48, v12, v48
	v_mul_f32_e32 v49, v13, v49
	v_mul_f32_e32 v50, v14, v50
	v_mul_f32_e32 v51, v15, v51
	v_mul_f32_e32 v60, v79, v77
	v_mul_f32_e32 v61, v79, v62
	v_mul_f32_e32 v62, v79, v78
	v_mul_f32_e32 v63, v79, v63
	v_mul_f32_e32 v60, v4, v60
	v_mul_f32_e32 v61, v5, v61
	v_mul_f32_e32 v62, v6, v62
	v_mul_f32_e32 v63, v7, v63
	v_cvt_pk_bf16_f32 v48, v48, v49
	v_cvt_pk_bf16_f32 v49, v50, v51
	v_cvt_pk_bf16_f32 v50, v60, v61
	v_cvt_pk_bf16_f32 v51, v62, v63
	global_store_dwordx4 v[66:67], v[48:51], off
	v_mul_f32_e32 v59, v79, v59
	v_mul_f32_e32 v59, v19, v59
	v_mul_f32_e32 v48, v79, v80
	v_mul_f32_e32 v49, v79, v56
	v_mul_f32_e32 v50, v79, v81
	v_mul_f32_e32 v51, v79, v57
	v_mul_f32_e32 v48, v8, v48
	v_mul_f32_e32 v49, v9, v49
	v_mul_f32_e32 v50, v10, v50
	v_mul_f32_e32 v51, v11, v51
	v_mul_f32_e32 v56, v79, v82
	v_mul_f32_e32 v57, v79, v58
	v_mul_f32_e32 v58, v79, v83
	v_mul_f32_e32 v56, v16, v56
	v_mul_f32_e32 v57, v17, v57
	v_mul_f32_e32 v58, v18, v58
	v_cvt_pk_bf16_f32 v48, v48, v49
	v_cvt_pk_bf16_f32 v49, v50, v51
	v_cvt_pk_bf16_f32 v50, v56, v57
	v_cvt_pk_bf16_f32 v51, v58, v59
	global_store_dwordx4 v[66:67], v[48:51], off offset:1024
	v_mul_f32_e32 v56, v79, v88
	v_mul_f32_e32 v57, v79, v89
	v_mul_f32_e32 v48, v79, v84
	v_mul_f32_e32 v49, v79, v85
	v_mul_f32_e32 v50, v79, v86
	v_mul_f32_e32 v51, v79, v87
	v_mul_f32_e32 v48, v20, v48
	v_mul_f32_e32 v49, v21, v49
	v_mul_f32_e32 v50, v22, v50
	v_mul_f32_e32 v51, v23, v51
	v_mul_f32_e32 v58, v79, v90
	v_mul_f32_e32 v59, v79, v91
	v_mul_f32_e32 v56, v24, v56
	v_mul_f32_e32 v57, v25, v57
	v_mul_f32_e32 v58, v26, v58
	v_mul_f32_e32 v59, v27, v59
	v_cvt_pk_bf16_f32 v48, v48, v49
	v_cvt_pk_bf16_f32 v49, v50, v51
	v_cvt_pk_bf16_f32 v50, v56, v57
	v_cvt_pk_bf16_f32 v51, v58, v59
	global_store_dwordx4 v[66:67], v[48:51], off offset:2048
	v_mul_f32_e32 v53, v79, v53
	v_mul_f32_e32 v52, v79, v52
	v_mul_f32_e32 v48, v79, v92
	v_mul_f32_e32 v49, v79, v93
	v_mul_f32_e32 v50, v79, v94
	v_mul_f32_e32 v51, v79, v95
	v_mul_f32_e32 v48, v28, v48
	v_mul_f32_e32 v49, v29, v49
	v_mul_f32_e32 v50, v30, v50
	v_mul_f32_e32 v51, v31, v51
	v_mul_f32_e32 v55, v79, v55
	v_mul_f32_e32 v54, v79, v54
	v_mul_f32_e32 v53, v32, v53
	v_mul_f32_e32 v52, v33, v52
	v_mul_f32_e32 v55, v34, v55
	v_mul_f32_e32 v54, v35, v54
	v_cvt_pk_bf16_f32 v48, v48, v49
	v_cvt_pk_bf16_f32 v49, v50, v51
	v_cvt_pk_bf16_f32 v50, v53, v52
	v_cvt_pk_bf16_f32 v51, v55, v54
	global_store_dwordx4 v[66:67], v[48:51], off offset:3072
	v_lshl_add_u64 v[66:67], v[66:67], 0, s[10:11]
	s_andn2_b64 vcc, exec, s[12:13]
	s_waitcnt vmcnt(4)
	v_mov_b32_e32 v60, v0
	v_mov_b32_e32 v61, v1
	v_mov_b32_e32 v62, v2
	v_mov_b32_e32 v63, v3
	v_mov_b32_e32 v56, v36
	v_mov_b32_e32 v57, v37
	v_mov_b32_e32 v58, v38
	v_mov_b32_e32 v59, v39
	v_mov_b32_e32 v52, v40
	v_mov_b32_e32 v53, v41
	v_mov_b32_e32 v54, v42
	v_mov_b32_e32 v55, v43
	v_mov_b32_e32 v48, v44
	v_mov_b32_e32 v49, v45
	v_mov_b32_e32 v50, v46
	v_mov_b32_e32 v51, v47
	s_cbranch_vccz .LBB0_1084

; template <bool F32OUT> __device__ __forceinline__ void norm_rows16(const bf16_t* X, const float* __restrict__ g, void* out, int rows) {
;     int bid_ = blockIdx.x, gdim_ = gridDim.x; asm volatile("" : "+s"(bid_), "+s"(gdim_));
;     int tix_ = threadIdx.x; asm volatile("" : "+v"(tix_));
;     const int lane = tix_ & 63, gw = __builtin_amdgcn_readfirstlane(bid_ * 8 + (tix_ >> 6)), GW = gdim_ * 8;
;     float4 ga[4], gb[4];
; #pragma unroll
;     for (int i = 0; i < 4; ++i) { ga[i] = *(const float4*)(g + 8 * lane + 512 * i); gb[i] = *(const float4*)(g + 8 * lane + 512 * i + 4); }
;     const int xl_ = bid_ & 7, chunk_ = rows >> 3, GWx = GW >> 3;
;     const int rend = chunk_ * (xl_ + 1);
;     int row = chunk_ * xl_ + ((bid_ >> 3) * 8 + (gw - bid_ * 8)); u32x4 x[4];
;     if (row < rend) {
; #pragma unroll
;         for (int i = 0; i < 4; ++i) x[i] = *(const u32x4*)(X + (size_t)row * DM + 8 * lane + 512 * i); }
;     while (row < rend) {
;         const int nrow = row + GWx; u32x4 xn[4];
;         if (nrow < rend) {
; #pragma unroll
;             for (int i = 0; i < 4; ++i) xn[i] = *(const u32x4*)(X + (size_t)nrow * DM + 8 * lane + 512 * i); }
.LBB0_1286:
	s_or_b64 exec, exec, s[4:5]
	s_mov_b64 s[6:7], s[0:1]
	s_mov_b32 s4, s40
	s_mov_b32 s5, s2
	s_waitcnt lgkmcnt(0)
	s_barrier
	s_mov_b32 s5, s2
	s_mov_b32 s4, s40
	v_mov_b32_e32 v2, v228
	s_lshl_b32 s8, s5, 3
	v_ashrrev_i32_e32 v0, 6, v2
	v_add_u32_e32 v0, s8, v0
	s_and_b32 s10, s5, -8
	v_readfirstlane_b32 s9, v0
	s_sub_i32 s8, s9, s8
	s_add_i32 s10, s8, s10
	s_cmpk_gt_i32 s10, 0x7ff
	s_cbranch_scc1 .LBB0_1291
	s_load_dwordx2 s[12:13], s[6:7], 0x28
	s_load_dwordx2 s[8:9], s[6:7], 0xa8
	v_lshlrev_b32_e32 v0, 3, v2
	v_and_b32_e32 v3, 0x1f8, v0
	v_lshlrev_b32_e32 v0, 2, v3
	v_mov_b32_e32 v1, 0
	s_lshl_b32 s5, s5, 11
	s_waitcnt lgkmcnt(0)
	v_lshl_add_u64 v[28:29], s[12:13], 0, v[0:1]
	s_mov_b64 s[6:7], 0x2000
	s_and_b32 s5, s5, 0x3800
	v_lshl_add_u64 v[20:21], v[28:29], 0, s[6:7]
	s_mov_b64 s[6:7], 0x3000
	s_add_i32 s12, s5, 0x800
	v_lshl_add_u64 v[30:31], v[28:29], 0, s[6:7]
	s_mov_b64 s[6:7], 0x3800
	s_add_u32 s14, s8, 0x2dd24000
	v_lshl_add_u64 v[38:39], v[28:29], 0, s[6:7]
	s_addc_u32 s15, s9, 0
	s_add_i32 s6, s10, s5
	v_add_co_u32_e32 v22, vcc, 0x2000, v28
	s_ashr_i32 s7, s6, 31
	s_nop 0
	v_addc_co_u32_e32 v23, vcc, 0, v29, vcc
	s_lshl_b64 s[10:11], s[6:7], 12
	v_add_co_u32_e32 v36, vcc, 0x3000, v28
	s_add_u32 s16, s14, s10
	s_nop 0
	v_addc_co_u32_e32 v37, vcc, 0, v29, vcc
	s_addc_u32 s17, s15, s11
	v_lshlrev_b32_e32 v0, 1, v3
	global_load_dwordx4 v[4:7], v[20:21], off offset:16
	global_load_dwordx4 v[8:11], v[20:21], off offset:2048
	global_load_dwordx4 v[12:15], v[22:23], off
	global_load_dwordx4 v[16:19], v[20:21], off offset:2064
	s_nop 0
	global_load_dwordx4 v[20:23], v[36:37], off
	global_load_dwordx4 v[24:27], v[30:31], off offset:16
	s_nop 0
	global_load_dwordx4 v[28:31], v[36:37], off offset:2048
	global_load_dwordx4 v[32:35], v[38:39], off offset:16
	global_load_dwordx4 v[60:63], v0, s[16:17]
	global_load_dwordx4 v[56:59], v0, s[16:17] offset:1024
	global_load_dwordx4 v[52:55], v0, s[16:17] offset:2048
	global_load_dwordx4 v[48:51], v0, s[16:17] offset:3072
	v_lshl_add_u64 v[64:65], s[14:15], 0, v[0:1]
	v_mbcnt_hi_u32_b32 v0, -1, v229
	v_and_b32_e32 v3, 64, v0
	v_add_u32_e32 v3, 64, v3
	v_xor_b32_e32 v36, 32, v0
	v_cmp_lt_i32_e32 vcc, v36, v3
	s_add_u32 s8, s8, s10
	s_addc_u32 s9, s9, s11
	v_cndmask_b32_e32 v36, v0, v36, vcc
	v_lshlrev_b32_e32 v68, 2, v36
	v_xor_b32_e32 v36, 16, v0
	v_cmp_lt_i32_e32 vcc, v36, v3
	s_ashr_i32 s5, s4, 31
	v_mov_b32_e32 v74, 0x358637bd
	v_cndmask_b32_e32 v36, v0, v36, vcc
	v_lshlrev_b32_e32 v69, 2, v36
	v_xor_b32_e32 v36, 8, v0
	v_cmp_lt_i32_e32 vcc, v36, v3
	v_mov_b32_e32 v37, v1
	v_mov_b32_e32 v38, v1
	v_cndmask_b32_e32 v36, v0, v36, vcc
	v_lshlrev_b32_e32 v70, 2, v36
	v_xor_b32_e32 v36, 4, v0
	v_cmp_lt_i32_e32 vcc, v36, v3
	v_mov_b32_e32 v39, v1
	v_mov_b32_e32 v40, v1
	v_cndmask_b32_e32 v36, v0, v36, vcc
	v_lshlrev_b32_e32 v71, 2, v36
	v_xor_b32_e32 v36, 2, v0
	v_cmp_lt_i32_e32 vcc, v36, v3
	v_mov_b32_e32 v41, v1
	v_mov_b32_e32 v42, v1
	v_cndmask_b32_e32 v36, v0, v36, vcc
	v_lshlrev_b32_e32 v72, 2, v36
	v_xor_b32_e32 v36, 1, v0
	v_cmp_lt_i32_e32 vcc, v36, v3
	v_mov_b32_e32 v43, v1
	v_mov_b32_e32 v44, v1
	v_cndmask_b32_e32 v0, v0, v36, vcc
	v_lshlrev_b32_e32 v73, 2, v0
	v_and_b32_e32 v0, 63, v2
	v_lshlrev_b32_e32 v0, 4, v0
	v_lshl_add_u64 v[2:3], s[8:9], 0, v[0:1]
	s_mov_b64 s[8:9], 0xc700000
	v_lshl_add_u64 v[66:67], v[2:3], 0, s[8:9]
	s_lshl_b64 s[8:9], s[4:5], 12
	s_mov_b32 s5, 0x800000
	v_mov_b32_e32 v0, v1
	v_mov_b32_e32 v2, v1
	v_mov_b32_e32 v3, v1
	v_mov_b32_e32 v36, v1
	v_mov_b32_e32 v45, v1
	v_mov_b32_e32 v46, v1
	v_mov_b32_e32 v47, v1
	s_waitcnt vmcnt(0)
	s_branch .LBB0_1289
; __device__ __forceinline__ unsigned cvt_pk_bf16(float lo, float hi) { unsigned r; asm volatile("v_cvt_pk_bf16_f32 %0, %1, %2" : "=v"(r) : "v"(lo), "v"(hi)); return r; }
; __device__ __forceinline__ float bflo(unsigned w) { return __uint_as_float(w << 16); }
; __device__ __forceinline__ float bfhi(unsigned w) { return __uint_as_float(w & 0xffff0000u); }
; template <bool F32OUT> __device__ __forceinline__ void norm_rows16(const bf16_t* X, const float* __restrict__ g, void* out, int rows) {
;     ...
;     while (row < rend) {
;         const int nrow = row + GWx; u32x4 xn[4];
;         if (nrow < rend) {
; #pragma unroll
;             for (int i = 0; i < 4; ++i) xn[i] = *(const u32x4*)(X + (size_t)nrow * DM + 8 * lane + 512 * i); }
;         float v[4][8]; float ss = 0.f;
; #pragma unroll
;         for (int i = 0; i < 4; ++i) { v[i][0] = bflo(x[i].x); v[i][1] = bfhi(x[i].x); v[i][2] = bflo(x[i].y); v[i][3] = bfhi(x[i].y); v[i][4] = bflo(x[i].z); v[i][5] = bfhi(x[i].z); v[i][6] = bflo(x[i].w); v[i][7] = bfhi(x[i].w);
; #pragma unroll
;             for (int e = 0; e < 8; ++e) ss += v[i][e] * v[i][e]; }
;         ss = wave_sum(ss);
;         const float rstd = rsqrtf(ss * (1.0f / DM) + 1e-6f);
; #pragma unroll
;         for (int i = 0; i < 4; ++i) {
;             const float o0 = v[i][0] * rstd * ga[i].x, o1 = v[i][1] * rstd * ga[i].y, o2 = v[i][2] * rstd * ga[i].z, o3 = v[i][3] * rstd * ga[i].w;
;             const float o4 = v[i][4] * rstd * gb[i].x, o5 = v[i][5] * rstd * gb[i].y, o6 = v[i][6] * rstd * gb[i].z, o7 = v[i][7] * rstd * gb[i].w;
;             if (F32OUT) { float* op = (float*)out + (size_t)row * DM + 8 * lane + 512 * i; *(float4*)op = make_float4(o0, o1, o2, o3); *(float4*)(op + 4) = make_float4(o4, o5, o6, o7); }
;             else { u32x4 w; w.x = cvt_pk_bf16(o0, o1); w.y = cvt_pk_bf16(o2, o3); w.z = cvt_pk_bf16(o4, o5); w.w = cvt_pk_bf16(o6, o7); *(u32x4*)((bf16_t*)out + (size_t)row * DM + 8 * lane + 512 * i) = w; }
;         }
; #pragma unroll
;         for (int i = 0; i < 4; ++i) x[i] = xn[i];
;         row = nrow;
;     }
.LBB0_1288:
	v_lshlrev_b32_e32 v75, 16, v60
	v_and_b32_e32 v60, 0xffff0000, v60
	v_mul_f32_e32 v79, v60, v60
	v_lshlrev_b32_e32 v76, 16, v61
	v_fmac_f32_e32 v79, v75, v75
	v_and_b32_e32 v61, 0xffff0000, v61
	v_fmac_f32_e32 v79, v76, v76
	v_lshlrev_b32_e32 v77, 16, v62
	v_fmac_f32_e32 v79, v61, v61
	v_and_b32_e32 v62, 0xffff0000, v62
	v_fmac_f32_e32 v79, v77, v77
	v_lshlrev_b32_e32 v78, 16, v63
	v_fmac_f32_e32 v79, v62, v62
	v_and_b32_e32 v63, 0xffff0000, v63
	v_fmac_f32_e32 v79, v78, v78
	v_fmac_f32_e32 v79, v63, v63
	v_lshlrev_b32_e32 v80, 16, v56
	v_and_b32_e32 v56, 0xffff0000, v56
	v_fmac_f32_e32 v79, v80, v80
	v_lshlrev_b32_e32 v81, 16, v57
	v_fmac_f32_e32 v79, v56, v56
	v_and_b32_e32 v57, 0xffff0000, v57
	v_fmac_f32_e32 v79, v81, v81
	v_lshlrev_b32_e32 v82, 16, v58
	v_fmac_f32_e32 v79, v57, v57
	v_and_b32_e32 v58, 0xffff0000, v58
	v_fmac_f32_e32 v79, v82, v82
	v_lshlrev_b32_e32 v83, 16, v59
	v_fmac_f32_e32 v79, v58, v58
	v_and_b32_e32 v59, 0xffff0000, v59
	v_fmac_f32_e32 v79, v83, v83
	v_fmac_f32_e32 v79, v59, v59
	v_lshlrev_b32_e32 v84, 16, v52
	v_and_b32_e32 v85, 0xffff0000, v52
	v_fmac_f32_e32 v79, v84, v84
	v_lshlrev_b32_e32 v86, 16, v53
	v_fmac_f32_e32 v79, v85, v85
	v_and_b32_e32 v87, 0xffff0000, v53
	v_fmac_f32_e32 v79, v86, v86
	v_lshlrev_b32_e32 v88, 16, v54
	v_fmac_f32_e32 v79, v87, v87
	v_and_b32_e32 v89, 0xffff0000, v54
	v_fmac_f32_e32 v79, v88, v88
	v_lshlrev_b32_e32 v90, 16, v55
	v_fmac_f32_e32 v79, v89, v89
	v_and_b32_e32 v91, 0xffff0000, v55
	v_fmac_f32_e32 v79, v90, v90
	v_fmac_f32_e32 v79, v91, v91
	v_lshlrev_b32_e32 v92, 16, v48
	v_and_b32_e32 v93, 0xffff0000, v48
	v_fmac_f32_e32 v79, v92, v92
	v_lshlrev_b32_e32 v94, 16, v49
	v_fmac_f32_e32 v79, v93, v93
	v_and_b32_e32 v95, 0xffff0000, v49
	v_fmac_f32_e32 v79, v94, v94
	v_and_b32_e32 v52, 0xffff0000, v50
	v_lshlrev_b32_e32 v53, 16, v50
	v_fmac_f32_e32 v79, v95, v95
	v_pk_mul_f32 v[48:49], v[52:53], v[52:53]
	v_and_b32_e32 v54, 0xffff0000, v51
	v_add_f32_e32 v49, v49, v79
	v_lshlrev_b32_e32 v55, 16, v51
	v_add_f32_e32 v50, v48, v49
	v_pk_mul_f32 v[48:49], v[54:55], v[54:55]
	s_nop 0
	v_add_f32_e32 v49, v49, v50
	v_add_f32_e32 v48, v48, v49
	ds_bpermute_b32 v49, v68, v48
	s_waitcnt lgkmcnt(0)
	v_add_f32_e32 v48, v48, v49
	ds_bpermute_b32 v49, v69, v48
	s_waitcnt lgkmcnt(0)
	v_add_f32_e32 v48, v48, v49
	ds_bpermute_b32 v49, v70, v48
	s_waitcnt lgkmcnt(0)
	v_add_f32_e32 v48, v48, v49
	ds_bpermute_b32 v49, v71, v48
	s_waitcnt lgkmcnt(0)
	v_add_f32_e32 v48, v48, v49
	ds_bpermute_b32 v49, v72, v48
	s_waitcnt lgkmcnt(0)
	v_add_f32_e32 v48, v48, v49
	ds_bpermute_b32 v49, v73, v48
	s_waitcnt lgkmcnt(0)
	v_add_f32_e32 v48, v48, v49
	v_fmamk_f32 v48, v48, 0x3a000000, v74
	v_mul_f32_e32 v49, 0x4b800000, v48
	v_cmp_gt_f32_e32 vcc, s5, v48
	s_nop 1
	v_cndmask_b32_e32 v48, v48, v49, vcc
	v_rsq_f32_e32 v48, v48
	s_nop 0
	v_mul_f32_e32 v49, 0x45800000, v48
	v_cndmask_b32_e32 v79, v48, v49, vcc
	v_mul_f32_e32 v48, v79, v75
	v_mul_f32_e32 v49, v79, v60
	v_mul_f32_e32 v50, v79, v76
	v_mul_f32_e32 v51, v79, v61
	v_mul_f32_e32 v48, v12, v48
	v_mul_f32_e32 v49, v13, v49
	v_mul_f32_e32 v50, v14, v50
	v_mul_f32_e32 v51, v15, v51
	v_mul_f32_e32 v60, v79, v77
	v_mul_f32_e32 v61, v79, v62
	v_mul_f32_e32 v62, v79, v78
	v_mul_f32_e32 v63, v79, v63
	v_mul_f32_e32 v60, v4, v60
	v_mul_f32_e32 v61, v5, v61
	v_mul_f32_e32 v62, v6, v62
	v_mul_f32_e32 v63, v7, v63
	v_cvt_pk_bf16_f32 v48, v48, v49
	v_cvt_pk_bf16_f32 v49, v50, v51
	v_cvt_pk_bf16_f32 v50, v60, v61
	v_cvt_pk_bf16_f32 v51, v62, v63
	global_store_dwordx4 v[66:67], v[48:51], off
	v_mul_f32_e32 v59, v79, v59
	v_mul_f32_e32 v59, v19, v59
	v_mul_f32_e32 v48, v79, v80
	v_mul_f32_e32 v49, v79, v56
	v_mul_f32_e32 v50, v79, v81
	v_mul_f32_e32 v51, v79, v57
	v_mul_f32_e32 v48, v8, v48
	v_mul_f32_e32 v49, v9, v49
	v_mul_f32_e32 v50, v10, v50
	v_mul_f32_e32 v51, v11, v51
	v_mul_f32_e32 v56, v79, v82
	v_mul_f32_e32 v57, v79, v58
	v_mul_f32_e32 v58, v79, v83
	v_mul_f32_e32 v56, v16, v56
	v_mul_f32_e32 v57, v17, v57
	v_mul_f32_e32 v58, v18, v58
	v_cvt_pk_bf16_f32 v48, v48, v49
	v_cvt_pk_bf16_f32 v49, v50, v51
	v_cvt_pk_bf16_f32 v50, v56, v57
	v_cvt_pk_bf16_f32 v51, v58, v59
	global_store_dwordx4 v[66:67], v[48:51], off offset:1024
	v_mul_f32_e32 v56, v79, v88
	v_mul_f32_e32 v57, v79, v89
	v_mul_f32_e32 v48, v79, v84
	v_mul_f32_e32 v49, v79, v85
	v_mul_f32_e32 v50, v79, v86
	v_mul_f32_e32 v51, v79, v87
	v_mul_f32_e32 v48, v20, v48
	v_mul_f32_e32 v49, v21, v49
	v_mul_f32_e32 v50, v22, v50
	v_mul_f32_e32 v51, v23, v51
	v_mul_f32_e32 v58, v79, v90
	v_mul_f32_e32 v59, v79, v91
	v_mul_f32_e32 v56, v24, v56
	v_mul_f32_e32 v57, v25, v57
	v_mul_f32_e32 v58, v26, v58
	v_mul_f32_e32 v59, v27, v59
	v_cvt_pk_bf16_f32 v48, v48, v49
	v_cvt_pk_bf16_f32 v49, v50, v51
	v_cvt_pk_bf16_f32 v50, v56, v57
	v_cvt_pk_bf16_f32 v51, v58, v59
	global_store_dwordx4 v[66:67], v[48:51], off offset:2048
	v_mul_f32_e32 v53, v79, v53
	v_mul_f32_e32 v52, v79, v52
	v_mul_f32_e32 v48, v79, v92
	v_mul_f32_e32 v49, v79, v93
	v_mul_f32_e32 v50, v79, v94
	v_mul_f32_e32 v51, v79, v95
	v_mul_f32_e32 v48, v28, v48
	v_mul_f32_e32 v49, v29, v49
	v_mul_f32_e32 v50, v30, v50
	v_mul_f32_e32 v51, v31, v51
	v_mul_f32_e32 v55, v79, v55
	v_mul_f32_e32 v54, v79, v54
	v_mul_f32_e32 v53, v32, v53
	v_mul_f32_e32 v52, v33, v52
	v_mul_f32_e32 v55, v34, v55
	v_mul_f32_e32 v54, v35, v54
	v_cvt_pk_bf16_f32 v48, v48, v49
	v_cvt_pk_bf16_f32 v49, v50, v51
	v_cvt_pk_bf16_f32 v50, v53, v52
	v_cvt_pk_bf16_f32 v51, v55, v54
	global_store_dwordx4 v[66:67], v[48:51], off offset:3072
	v_lshl_add_u64 v[66:67], v[66:67], 0, s[8:9]
	s_andn2_b64 vcc, exec, s[10:11]
	s_waitcnt vmcnt(4)
	v_mov_b32_e32 v60, v0
	v_mov_b32_e32 v61, v1
	v_mov_b32_e32 v62, v2
	v_mov_b32_e32 v63, v3
	v_mov_b32_e32 v56, v36
	v_mov_b32_e32 v57, v37
	v_mov_b32_e32 v58, v38
	v_mov_b32_e32 v59, v39
	v_mov_b32_e32 v52, v40
	v_mov_b32_e32 v53, v41
	v_mov_b32_e32 v54, v42
	v_mov_b32_e32 v55, v43
	v_mov_b32_e32 v48, v44
	v_mov_b32_e32 v49, v45
	v_mov_b32_e32 v50, v46
	v_mov_b32_e32 v51, v47
	s_cbranch_vccz .LBB0_1291

; template <bool F32OUT> __device__ __forceinline__ void norm_rows16(const bf16_t* X, const float* __restrict__ g, void* out, int rows) {
;     int bid_ = blockIdx.x, gdim_ = gridDim.x; asm volatile("" : "+s"(bid_), "+s"(gdim_));
;     int tix_ = threadIdx.x; asm volatile("" : "+v"(tix_));
;     const int lane = tix_ & 63, gw = __builtin_amdgcn_readfirstlane(bid_ * 8 + (tix_ >> 6)), GW = gdim_ * 8;
;     float4 ga[4], gb[4];
; #pragma unroll
;     for (int i = 0; i < 4; ++i) { ga[i] = *(const float4*)(g + 8 * lane + 512 * i); gb[i] = *(const float4*)(g + 8 * lane + 512 * i + 4); }
;     const int xl_ = bid_ & 7, chunk_ = rows >> 3, GWx = GW >> 3;
;     const int rend = chunk_ * (xl_ + 1);
;     int row = chunk_ * xl_ + ((bid_ >> 3) * 8 + (gw - bid_ * 8)); u32x4 x[4];
;     if (row < rend) {
; #pragma unroll
;         for (int i = 0; i < 4; ++i) x[i] = *(const u32x4*)(X + (size_t)row * DM + 8 * lane + 512 * i); }
;     while (row < rend) {
;         const int nrow = row + GWx; u32x4 xn[4];
;         if (nrow < rend) {
; #pragma unroll
;             for (int i = 0; i < 4; ++i) xn[i] = *(const u32x4*)(X + (size_t)nrow * DM + 8 * lane + 512 * i); }
.LBB0_1914:
	s_or_b64 exec, exec, s[4:5]
	s_mov_b64 s[6:7], s[0:1]
	s_mov_b32 s4, s40
	s_mov_b32 s5, s2
	s_waitcnt lgkmcnt(0)
	s_barrier
	s_mov_b32 s5, s2
	s_mov_b32 s4, s40
	v_mov_b32_e32 v2, v228
	s_lshl_b32 s8, s5, 3
	v_ashrrev_i32_e32 v0, 6, v2
	v_add_u32_e32 v0, s8, v0
	s_and_b32 s10, s5, -8
	v_readfirstlane_b32 s9, v0
	s_sub_i32 s8, s9, s8
	s_add_i32 s10, s8, s10
	s_cmpk_gt_i32 s10, 0x7ff
	s_cbranch_scc1 .LBB0_1919
	s_load_dwordx2 s[12:13], s[6:7], 0x80
	s_load_dwordx2 s[8:9], s[6:7], 0xa8
	v_lshlrev_b32_e32 v0, 3, v2
	v_and_b32_e32 v3, 0x1f8, v0
	v_lshlrev_b32_e32 v0, 2, v3
	v_mov_b32_e32 v1, 0
	s_lshl_b32 s5, s5, 11
	s_waitcnt lgkmcnt(0)
	v_lshl_add_u64 v[28:29], s[12:13], 0, v[0:1]
	s_mov_b64 s[6:7], 0x2000
	s_and_b32 s5, s5, 0x3800
	v_lshl_add_u64 v[20:21], v[28:29], 0, s[6:7]
	s_mov_b64 s[6:7], 0x3000
	s_add_i32 s12, s5, 0x800
	v_lshl_add_u64 v[30:31], v[28:29], 0, s[6:7]
	s_mov_b64 s[6:7], 0x3800
	s_add_u32 s14, s8, 0x2dd24000
	v_lshl_add_u64 v[38:39], v[28:29], 0, s[6:7]
	s_addc_u32 s15, s9, 0
	s_add_i32 s6, s10, s5
	v_add_co_u32_e32 v22, vcc, 0x2000, v28
	s_ashr_i32 s7, s6, 31
	s_nop 0
	v_addc_co_u32_e32 v23, vcc, 0, v29, vcc
	s_lshl_b64 s[10:11], s[6:7], 12
	v_add_co_u32_e32 v36, vcc, 0x3000, v28
	s_add_u32 s16, s14, s10
	s_nop 0
	v_addc_co_u32_e32 v37, vcc, 0, v29, vcc
	s_addc_u32 s17, s15, s11
	v_lshlrev_b32_e32 v0, 1, v3
	global_load_dwordx4 v[4:7], v[20:21], off offset:16
	global_load_dwordx4 v[8:11], v[20:21], off offset:2048
	global_load_dwordx4 v[12:15], v[22:23], off
	global_load_dwordx4 v[16:19], v[20:21], off offset:2064
	s_nop 0
	global_load_dwordx4 v[20:23], v[36:37], off
	global_load_dwordx4 v[24:27], v[30:31], off offset:16
	s_nop 0
	global_load_dwordx4 v[28:31], v[36:37], off offset:2048
	global_load_dwordx4 v[32:35], v[38:39], off offset:16
	global_load_dwordx4 v[60:63], v0, s[16:17]
	global_load_dwordx4 v[56:59], v0, s[16:17] offset:1024
	global_load_dwordx4 v[52:55], v0, s[16:17] offset:2048
	global_load_dwordx4 v[48:51], v0, s[16:17] offset:3072
	v_lshl_add_u64 v[64:65], s[14:15], 0, v[0:1]
	v_mbcnt_hi_u32_b32 v0, -1, v229
	v_and_b32_e32 v3, 64, v0
	v_add_u32_e32 v3, 64, v3
	v_xor_b32_e32 v36, 32, v0
	v_cmp_lt_i32_e32 vcc, v36, v3
	s_add_u32 s8, s8, s10
	s_addc_u32 s9, s9, s11
	v_cndmask_b32_e32 v36, v0, v36, vcc
	v_lshlrev_b32_e32 v68, 2, v36
	v_xor_b32_e32 v36, 16, v0
	v_cmp_lt_i32_e32 vcc, v36, v3
	s_ashr_i32 s5, s4, 31
	v_mov_b32_e32 v74, 0x358637bd
	v_cndmask_b32_e32 v36, v0, v36, vcc
	v_lshlrev_b32_e32 v69, 2, v36
	v_xor_b32_e32 v36, 8, v0
	v_cmp_lt_i32_e32 vcc, v36, v3
	v_mov_b32_e32 v37, v1
	v_mov_b32_e32 v38, v1
	v_cndmask_b32_e32 v36, v0, v36, vcc
	v_lshlrev_b32_e32 v70, 2, v36
	v_xor_b32_e32 v36, 4, v0
	v_cmp_lt_i32_e32 vcc, v36, v3
	v_mov_b32_e32 v39, v1
	v_mov_b32_e32 v40, v1
	v_cndmask_b32_e32 v36, v0, v36, vcc
	v_lshlrev_b32_e32 v71, 2, v36
	v_xor_b32_e32 v36, 2, v0
	v_cmp_lt_i32_e32 vcc, v36, v3
	v_mov_b32_e32 v41, v1
	v_mov_b32_e32 v42, v1
	v_cndmask_b32_e32 v36, v0, v36, vcc
	v_lshlrev_b32_e32 v72, 2, v36
	v_xor_b32_e32 v36, 1, v0
	v_cmp_lt_i32_e32 vcc, v36, v3
	v_mov_b32_e32 v43, v1
	v_mov_b32_e32 v44, v1
	v_cndmask_b32_e32 v0, v0, v36, vcc
	v_lshlrev_b32_e32 v73, 2, v0
	v_and_b32_e32 v0, 63, v2
	v_lshlrev_b32_e32 v0, 4, v0
	v_lshl_add_u64 v[2:3], s[8:9], 0, v[0:1]
	s_mov_b64 s[8:9], 0xc700000
	v_lshl_add_u64 v[66:67], v[2:3], 0, s[8:9]
	s_lshl_b64 s[8:9], s[4:5], 12
	s_mov_b32 s5, 0x800000
	v_mov_b32_e32 v0, v1
	v_mov_b32_e32 v2, v1
	v_mov_b32_e32 v3, v1
	v_mov_b32_e32 v36, v1
	v_mov_b32_e32 v45, v1
	v_mov_b32_e32 v46, v1
	v_mov_b32_e32 v47, v1
	s_waitcnt vmcnt(0)
	s_branch .LBB0_1917
